# P0 x->bf16 conversion loop: 4 loads in flight with counted vmcnt instead of serialized vmcnt(0)
# speedup vs baseline: 1.0064x; 1.0064x over previous
.LBB0_55:
	global_load_dwordx4 v[6:9], v[2:3], off offset:-2048
	global_load_dwordx4 v[14:17], v[2:3], off offset:-1024
	global_load_dwordx4 v[18:21], v[2:3], off
	global_load_dwordx4 v[22:25], v[2:3], off offset:1024
	s_add_i32 s4, s4, s52
	v_lshl_add_u64 v[2:3], v[2:3], 0, s[2:3]
	s_waitcnt vmcnt(3)
	v_cvt_pk_bf16_f32 v6, v6, v7
	v_cvt_pk_bf16_f32 v7, v8, v9
	global_store_dwordx2 v[4:5], v[6:7], off offset:-1536
	s_waitcnt vmcnt(3)
	v_cvt_pk_bf16_f32 v14, v14, v15
	v_cvt_pk_bf16_f32 v15, v16, v17
	global_store_dwordx2 v[4:5], v[14:15], off offset:-1024
	s_waitcnt vmcnt(3)
	v_cvt_pk_bf16_f32 v18, v18, v19
	v_cvt_pk_bf16_f32 v19, v20, v21
	global_store_dwordx2 v[4:5], v[18:19], off offset:-512
	s_waitcnt vmcnt(3)
	v_cvt_pk_bf16_f32 v22, v22, v23
	v_cvt_pk_bf16_f32 v23, v24, v25
	global_store_dwordx2 v[4:5], v[22:23], off
	v_lshl_add_u64 v[4:5], v[4:5], 0, s[0:1]
	s_cmpk_gt_i32 s4, 0x7fff
	s_cbranch_scc0 .LBB0_55
